# P2b first-unit register prefetch of waves 1-7 issued before they park at the P2a->P2b grid barrier (inputs are final since P1a)
# speedup vs baseline: 1.0021x; 1.0021x over previous
; __device__ __forceinline__ void gla_prep_phase(LAS unsigned char* lds, const GlaPrepArgs& A, int bid, int G) {
;     ...
;     int unit = bid;
;     if (unit < nunits) GLA_PREFETCH(unit);
; __device__ __forceinline__ void xcd_barrier(const XcdBarrier& b) {
;     asm volatile("s_waitcnt vmcnt(0)" ::: "memory");
;     __syncthreads();
;     if (threadIdx.x == 0) {
;         unsigned* bar = b.bar;
;         __builtin_amdgcn_s_waitcnt(0);
;         unsigned nloc = b.st[0], nx = b.st[1];
;         if (nloc == 0u) { xcd_barrier_complete(bar, b.x, nloc, nx); b.st[0] = nloc; b.st[1] = nx; }
.LBB0_362:
	v_readlane_b32 s2, v254, 48
	s_or_b32 s34, s2, 3
	s_cmp_ge_i32 s34, s87
	s_cbranch_scc1 .LBB0_416
	s_waitcnt vmcnt(0)
	s_waitcnt lgkmcnt(0)
	s_barrier
	v_readfirstlane_b32 s98, v0
	s_nop 0
	s_nop 0
	s_cmp_eq_u32 s98, 0
	s_cbranch_scc1 .Lp2b_early_done
	v_ashrrev_i32_e32 v72, 3, v0
	v_readlane_b32 s4, v251, 45
	v_ashrrev_i32_e32 v73, 31, v72
	v_readlane_b32 s5, v251, 46
	v_readlane_b32 s76, v251, 25
	v_readlane_b32 s77, v251, 26
	v_lshl_add_u64 v[4:5], s[4:5], 0, v[72:73]
	v_lshlrev_b64 v[4:5], 8, v[4:5]
	v_lshlrev_b32_e32 v3, 4, v0
	v_lshl_add_u64 v[4:5], s[76:77], 0, v[4:5]
	v_and_b32_e32 v130, 0x70, v3
	v_ashrrev_i32_e32 v74, 5, v0
	v_lshl_add_u64 v[4:5], v[4:5], 0, v[130:131]
	v_readlane_b32 s6, v251, 49
	v_ashrrev_i32_e32 v75, 31, v74
	global_load_dwordx4 v[34:37], v[4:5], off offset:128
	v_and_b32_e32 v4, 0x1f0, v3
	v_mov_b32_e32 v5, v131
	v_readlane_b32 s7, v251, 50
	v_lshl_add_u64 v[8:9], s[4:5], 0, v[74:75]
	v_add_u32_e32 v12, 0x200, v0
	v_lshl_add_u64 v[6:7], s[6:7], 0, v[4:5]
	v_lshlrev_b64 v[8:9], 11, v[8:9]
	v_ashrrev_i32_e32 v76, 5, v12
	v_lshl_add_u64 v[8:9], v[6:7], 0, v[8:9]
	v_ashrrev_i32_e32 v77, 31, v76
	global_load_dwordx4 v[38:41], v[8:9], off
	v_lshl_add_u64 v[8:9], s[4:5], 0, v[76:77]
	v_lshlrev_b64 v[8:9], 11, v[8:9]
	v_lshl_add_u64 v[8:9], v[6:7], 0, v[8:9]
	global_load_dwordx4 v[42:45], v[8:9], off
	v_add_u32_e32 v8, 0x400, v0
	v_ashrrev_i32_e32 v78, 5, v8
	v_ashrrev_i32_e32 v79, 31, v78
	v_lshl_add_u64 v[8:9], s[4:5], 0, v[78:79]
	v_lshlrev_b64 v[8:9], 11, v[8:9]
	v_lshl_add_u64 v[8:9], v[6:7], 0, v[8:9]
	global_load_dwordx4 v[46:49], v[8:9], off
	v_add_u32_e32 v8, 0x600, v0
	v_ashrrev_i32_e32 v80, 5, v8
	v_ashrrev_i32_e32 v81, 31, v80
	v_lshl_add_u64 v[8:9], s[4:5], 0, v[80:81]
	v_lshlrev_b64 v[8:9], 11, v[8:9]
	v_ashrrev_i32_e32 v82, 4, v0
	v_lshl_add_u64 v[6:7], v[6:7], 0, v[8:9]
	v_readlane_b32 s6, v251, 53
	v_ashrrev_i32_e32 v83, 31, v82
	global_load_dwordx4 v[50:53], v[6:7], off
	v_and_b32_e32 v6, 0xf0, v3
	v_mov_b32_e32 v7, v131
	v_readlane_b32 s7, v251, 54
	v_lshl_add_u64 v[10:11], s[4:5], 0, v[82:83]
	v_lshlrev_b64 v[10:11], 11, v[10:11]
	v_lshl_add_u64 v[8:9], s[6:7], 0, v[6:7]
	v_ashrrev_i32_e32 v84, 4, v12
	v_lshl_add_u64 v[10:11], v[8:9], 0, v[10:11]
	v_ashrrev_i32_e32 v85, 31, v84
	global_load_dwordx4 v[54:57], v[10:11], off
	global_load_dwordx4 v[58:61], v[10:11], off offset:1024
	v_lshl_add_u64 v[10:11], s[4:5], 0, v[84:85]
	v_lshlrev_b64 v[10:11], 11, v[10:11]
	v_lshl_add_u64 v[8:9], v[8:9], 0, v[10:11]
	global_load_dwordx4 v[62:65], v[8:9], off
	global_load_dwordx4 v[66:69], v[8:9], off offset:1024
.Lp2b_early_done:
	s_and_saveexec_b64 s[2:3], s[88:89]
	s_cbranch_execz .LBB0_415
	v_readlane_b32 s4, v252, 60
	s_waitcnt vmcnt(0) expcnt(0) lgkmcnt(0)
	s_nop 0
	v_mov_b32_e32 v2, s4
	ds_read_b32 v4, v2
	v_readlane_b32 s4, v252, 61
	s_waitcnt lgkmcnt(0)
	v_cmp_ne_u32_e32 vcc, 0, v4
	v_mov_b32_e32 v2, s4
	ds_read_b32 v2, v2
	s_cbranch_vccnz .LBB0_379
	v_readlane_b32 s6, v250, 8
	v_readlane_b32 s7, v250, 9
	s_load_dwordx2 s[4:5], s[6:7], 0x4
	s_mov_b32 s39, 1
	s_waitcnt lgkmcnt(0)
	s_mul_i32 s38, s4, s93
	s_mul_i32 s38, s38, s5
	s_branch .LBB0_367

; #define LAS __attribute__((address_space(3)))
; __device__ __forceinline__ void gla_prep_phase(LAS unsigned char* lds, const GlaPrepArgs& A, int bid, int G) {
;     using namespace gla;
;     int tid_l = threadIdx.x; asm volatile("" : "+v"(tid_l));
;     const int tid = tid_l, lane = tid & 63, w = __builtin_amdgcn_readfirstlane(tid >> 6);
;     const int nunits = A.nseq * 4 * NCH;
;     f32x4 pr; v4u pv[4], pq[2], pk[2];
;     ...
;     int unit = bid;
;     if (unit < nunits) GLA_PREFETCH(unit);
.LBB0_418:
	s_andn2_b64 vcc, exec, s[2:3]
	s_cbranch_vccnz .LBB0_489
	v_readlane_b32 s2, v251, 43
	v_writelane_b32 v254, s42, 55
	v_mov_b32_e32 v70, v0
	v_readlane_b32 s3, v251, 44
	v_writelane_b32 v254, s43, 56
	s_andn2_b64 vcc, exec, s[2:3]
	v_readfirstlane_b32 s3, v70
	s_cbranch_vccnz .LBB0_434
	s_cmp_lg_u32 s3, 0
	s_cbranch_scc1 .Lp2b_pre_done
	v_ashrrev_i32_e32 v72, 3, v70
	v_readlane_b32 s4, v251, 45
	v_ashrrev_i32_e32 v73, 31, v72
	v_readlane_b32 s5, v251, 46
	v_readlane_b32 s76, v251, 25
	v_readlane_b32 s77, v251, 26
	s_waitcnt vmcnt(0)
	v_lshl_add_u64 v[4:5], s[4:5], 0, v[72:73]
	v_lshlrev_b64 v[4:5], 8, v[4:5]
	v_lshlrev_b32_e32 v3, 4, v70
	v_lshl_add_u64 v[4:5], s[76:77], 0, v[4:5]
	v_and_b32_e32 v130, 0x70, v3
	v_ashrrev_i32_e32 v74, 5, v70
	v_lshl_add_u64 v[4:5], v[4:5], 0, v[130:131]
	v_readlane_b32 s6, v251, 49
	v_ashrrev_i32_e32 v75, 31, v74
	global_load_dwordx4 v[34:37], v[4:5], off offset:128
	v_and_b32_e32 v4, 0x1f0, v3
	v_mov_b32_e32 v5, v131
	v_readlane_b32 s7, v251, 50
	v_lshl_add_u64 v[8:9], s[4:5], 0, v[74:75]
	v_add_u32_e32 v12, 0x200, v70
	v_lshl_add_u64 v[6:7], s[6:7], 0, v[4:5]
	v_lshlrev_b64 v[8:9], 11, v[8:9]
	v_ashrrev_i32_e32 v76, 5, v12
	v_lshl_add_u64 v[8:9], v[6:7], 0, v[8:9]
	v_ashrrev_i32_e32 v77, 31, v76
	global_load_dwordx4 v[38:41], v[8:9], off
	v_lshl_add_u64 v[8:9], s[4:5], 0, v[76:77]
	v_lshlrev_b64 v[8:9], 11, v[8:9]
	v_lshl_add_u64 v[8:9], v[6:7], 0, v[8:9]
	global_load_dwordx4 v[42:45], v[8:9], off
	v_add_u32_e32 v8, 0x400, v70
	v_ashrrev_i32_e32 v78, 5, v8
	v_ashrrev_i32_e32 v79, 31, v78
	v_lshl_add_u64 v[8:9], s[4:5], 0, v[78:79]
	v_lshlrev_b64 v[8:9], 11, v[8:9]
	v_lshl_add_u64 v[8:9], v[6:7], 0, v[8:9]
	global_load_dwordx4 v[46:49], v[8:9], off
	v_add_u32_e32 v8, 0x600, v70
	v_ashrrev_i32_e32 v80, 5, v8
	v_ashrrev_i32_e32 v81, 31, v80
	v_lshl_add_u64 v[8:9], s[4:5], 0, v[80:81]
	v_lshlrev_b64 v[8:9], 11, v[8:9]
	v_ashrrev_i32_e32 v82, 4, v70
	v_lshl_add_u64 v[6:7], v[6:7], 0, v[8:9]
	v_readlane_b32 s6, v251, 53
	v_ashrrev_i32_e32 v83, 31, v82
	global_load_dwordx4 v[50:53], v[6:7], off
	v_and_b32_e32 v6, 0xf0, v3
	v_mov_b32_e32 v7, v131
	v_readlane_b32 s7, v251, 54
	v_lshl_add_u64 v[10:11], s[4:5], 0, v[82:83]
	v_lshlrev_b64 v[10:11], 11, v[10:11]
	v_lshl_add_u64 v[8:9], s[6:7], 0, v[6:7]
	v_ashrrev_i32_e32 v84, 4, v12
	v_lshl_add_u64 v[10:11], v[8:9], 0, v[10:11]
	v_ashrrev_i32_e32 v85, 31, v84
	global_load_dwordx4 v[54:57], v[10:11], off
	global_load_dwordx4 v[58:61], v[10:11], off offset:1024
	v_lshl_add_u64 v[10:11], s[4:5], 0, v[84:85]
	v_lshlrev_b64 v[10:11], 11, v[10:11]
	v_lshl_add_u64 v[8:9], v[8:9], 0, v[10:11]
	global_load_dwordx4 v[62:65], v[8:9], off
	global_load_dwordx4 v[66:69], v[8:9], off offset:1024
.Lp2b_pre_done:
	s_ashr_i32 s2, s3, 6
	s_cmp_gt_i32 s2, 3
	v_lshrrev_b32_e32 v12, 2, v70
	v_and_b32_e32 v180, 0x11f, v70
	v_and_b32_e32 v181, 0xc0, v70
	v_lshrrev_b32_e32 v181, 1, v181
	v_or_b32_e32 v180, v180, v181
	v_and_b32_e32 v181, 32, v70
	v_lshl_or_b32 v180, v181, 2, v180
	s_nop 0
	v_and_b32_e32 v86, 0x7f, v180
	v_readlane_b32 s4, v254, 2
	s_cselect_b64 s[70:71], -1, 0
	s_lshl_b32 s5, s2, 4
	v_and_b32_e32 v12, 8, v12
	v_lshl_add_u32 v98, v180, 2, s4
	v_lshl_add_u32 v99, v86, 2, s4
	s_movk_i32 s4, 0x80
	v_and_or_b32 v13, s5, 48, v12
	v_readlane_b32 s5, v254, 3
	v_cmp_gt_u32_e64 s[36:37], s4, v180
	s_add_i32 s4, s2, -4
	v_mov_b32_e32 v14, s5
	s_ashr_i32 s5, s3, 7
	s_and_b32 s6, s2, 1
	s_cmp_ge_i32 s5, s6
	s_cselect_b64 s[38:39], -1, 0
	s_lshl_b32 s7, s5, 5
	v_readlane_b32 s34, v254, 1
	v_writelane_b32 v254, s38, 53
	s_cmp_le_i32 s5, s6
	v_lshlrev_b32_e32 v20, 1, v70
	v_writelane_b32 v254, s39, 54
	s_cselect_b64 s[38:39], -1, 0
	s_andn2_b32 s3, s3, 63
	v_and_b32_e32 v20, 62, v20
	s_add_i32 s3, s34, s3
	v_add_u32_e32 v20, s3, v20
	s_ashr_i32 s3, s2, 31
	s_lshl_b64 s[74:75], s[2:3], 12
	s_movk_i32 s3, 0x210
	v_ashrrev_i32_e32 v10, 7, v180
	v_writelane_b32 v254, s38, 57
	v_mul_lo_u32 v22, v74, s3
	v_mul_lo_u32 v23, v76, s3
	v_mul_lo_u32 v24, v78, s3
	v_mul_lo_u32 v25, v80, s3
	s_movk_i32 s3, 0x1100
	v_and_b32_e32 v181, 3, v70
	v_bfe_u32 v182, v70, 3, 2
	v_lshl_or_b32 v181, v182, 2, v181
	v_bfe_u32 v182, v70, 2, 1
	v_lshl_or_b32 v181, v182, 4, v181
	v_bfe_u32 v182, v70, 8, 1
	v_lshl_or_b32 v181, v182, 5, v181
	v_bfe_u32 v182, v70, 5, 1
	v_lshlrev_b32_e32 v182, 5, v182
	v_lshl_or_b32 v87, v181, 7, v182
	v_and_b32_e32 v11, 0x3fffff80, v180
	v_writelane_b32 v254, s39, 58
	v_cmp_lt_i32_e64 s[38:39], 0, v10
	v_cmp_gt_i32_e64 s[40:41], 0, v10
	v_cmp_lt_i32_e64 s[42:43], 1, v10
	v_cmp_gt_i32_e64 s[44:45], 1, v10
	v_cmp_lt_i32_e64 s[46:47], 2, v10
	v_cmp_gt_i32_e64 s[48:49], 2, v10
	v_cmp_lt_i32_e64 s[50:51], 3, v10
	v_cmp_gt_i32_e64 s[52:53], 3, v10
	v_mul_lo_u32 v10, v10, s3
	s_lshl_b32 s3, s4, 2
	v_lshl_add_u32 v100, v11, 2, v99
	v_and_b32_e32 v11, 31, v70
	s_and_b32 s3, s3, 0xfffffe0
	v_or_b32_e32 v28, s3, v11
	s_lshl_b32 s3, s4, 5
	s_movk_i32 s54, 0x110
	s_and_b32 s3, s3, 0xe0
	v_mul_lo_u32 v28, v28, s54
	s_add_i32 s3, s3, 0
	v_add_u32_e32 v28, s3, v28
	s_lshl_b32 s3, s2, 2
	s_and_b32 s3, s3, 0xfffffe0
	v_or_b32_e32 v29, s3, v11
	s_lshl_b32 s3, s2, 5
	s_and_b32 s3, s3, 0xe0
	v_readlane_b32 s5, v254, 4
	v_lshrrev_b32_e32 v21, 1, v70
	v_mul_lo_u32 v29, v29, s54
	s_add_i32 s3, s3, 0
	v_lshl_or_b32 v16, s6, 5, v11
	v_mov_b32_e32 v18, s5
	v_readlane_b32 s5, v254, 5
	v_and_b32_e32 v21, 16, v21
	v_add_u32_e32 v29, s3, v29
	s_add_i32 s3, s2, 4
; __device__ __forceinline__ void gla_prep_phase(LAS unsigned char* lds, const GlaPrepArgs& A, int bid, int G) {
;     ...
;     *(LAS f32x4*)(lds + L_R + (tid >> 3) * 128 + (tid & 7) * 16) = pr;
; #pragma unroll
;     for (int i = 0; i < 4; ++i) { const int id = i * 512 + tid; *(LAS v4u*)(lds + L_V + (id >> 5) * VS_ + (id & 31) * 16) = pv[i]; }
; #pragma unroll
;     for (int i = 0; i < 2; ++i) { const int id = i * 512 + tid; *(LAS v4u*)(lds + L_QGF + (id >> 4) * QS_ + (id & 15) * 16) = pq[i]; *(LAS v4u*)(lds + L_KGF + (id >> 4) * QS_ + (id & 15) * 16) = pk[i]; }
;     ...
;             const int o = (pg * 16 + pp) * QS_ + dd * 2;
;             const float qv = bf2f(*(const LAS unsigned short*)(lds + L_QGF + o)) * QSCALE, kv = bf2f(*(const LAS unsigned short*)(lds + L_KGF + o));
;             const float ef = __builtin_amdgcn_exp2f(lf[pp] + offf), eb = __builtin_amdgcn_exp2f(lb[pp] + offb);
;             const float rf = __builtin_amdgcn_rcpf(ef), rb = __builtin_amdgcn_rcpf(eb);
;             *(LAS unsigned short*)(lds + L_QGF + o) = (unsigned short)(pkbf(qv * ef, 0.f) & 0xffffu);
;             *(LAS unsigned short*)(lds + L_KGF + o) = (unsigned short)(pkbf(kv * rf, 0.f) & 0xffffu);
;             *(LAS unsigned short*)(lds + L_KDF + o) = (unsigned short)(pkbf(kv * rf * eglf, 0.f) & 0xffffu);
;             *(LAS unsigned short*)(lds + L_QGB + o) = (unsigned short)(pkbf(qv * eb, 0.f) & 0xffffu);
;             *(LAS unsigned short*)(lds + L_KGB + o) = (unsigned short)(pkbf(kv * rb, 0.f) & 0xffffu);
;             *(LAS unsigned short*)(lds + L_KDB + o) = (unsigned short)(pkbf(kv * rb * eglb, 0.f) & 0xffffu);
;         }
;     }
;     LBAR();
;     { const int un = unit + G; if (un < nunits) GLA_PREFETCH(un); }
;     if (w < 4) {
;         const int rt = w >> 1, ct = w & 1, r = lane & 31, hh = lane >> 5;
;         f32x16 af = zero16(), ab = zero16();
;         if (rt >= ct) { const LAS unsigned char* ia = lds + L_QGF + (32 * rt + r) * QS_ + 16 * hh; const LAS unsigned char* ib = lds + L_KGF + (32 * ct + r) * QS_ + 16 * hh;
; #pragma unroll
;             for (int ks = 0; ks < 8; ++ks) af = MFMA32(*(const LAS bf16x8*)(ia + 32 * ks), *(const LAS bf16x8*)(ib + 32 * ks), af); }
;         if (rt <= ct) { const LAS unsigned char* ia = lds + L_QGB + (32 * rt + r) * QS_ + 16 * hh; const LAS unsigned char* ib = lds + L_KGB + (32 * ct + r) * QS_ + 16 * hh;
; #pragma unroll
	v_lshl_add_u32 v19, v16, 1, s5
	v_add_u32_e32 v21, s5, v21
	s_lshl_b32 s5, s3, 2
	s_and_b32 s5, s5, 0xfffffe0
	v_or_b32_e32 v30, s5, v11
	s_lshl_b32 s5, s3, 5
	s_and_b32 s5, s5, 0xe0
	v_add_u32_e32 v8, s34, v4
	s_lshl_b32 s34, s4, 10
	v_mul_lo_u32 v30, v30, s54
	s_add_i32 s5, s5, 0
	s_lshl_b32 s4, s4, 3
	s_lshl_b32 s72, s2, 12
	s_lshl_b32 s84, s2, 10
	v_add_u32_e32 v30, s5, v30
	s_add_i32 s5, s2, 8
	s_and_b32 s4, s4, 0x7fffffe0
	s_lshl_b32 s2, s2, 3
	v_or_b32_e32 v32, s4, v11
	s_and_b32 s2, s2, 0x7fffffe0
	v_lshlrev_b32_e32 v103, 1, v32
	v_or_b32_e32 v32, s2, v11
	s_lshl_b32 s2, s3, 3
	s_and_b32 s2, s2, 0x7fffffe0
	v_mad_u32_u24 v101, v13, s54, 0
	v_mad_u32_u24 v102, v13, s54, v14
	v_bfe_u32 v13, v70, 5, 1
	v_lshlrev_b32_e32 v104, 1, v32
	v_or_b32_e32 v32, s2, v11
	s_lshl_b32 s2, s5, 3
	v_lshlrev_b32_e32 v15, 4, v13
	s_and_b32 s2, s2, 0x7fffffe0
	v_lshl_or_b32 v13, v13, 2, s7
	s_lshl_b32 s85, s3, 10
	v_lshlrev_b32_e32 v105, 1, v32
	v_or_b32_e32 v32, s2, v11
	v_cmp_gt_i32_e64 s[2:3], v13, v16
	v_or_b32_e32 v33, 1, v13
	v_lshlrev_b32_e32 v106, 1, v32
	v_writelane_b32 v255, s2, 1
	s_lshl_b32 s6, s5, 2
	s_and_b32 s6, s6, 0xfffffe0
	v_writelane_b32 v255, s3, 2
	s_movk_i32 s2, 0x90
	v_mul_lo_u32 v32, v13, s2
	v_cmp_lt_i32_e64 s[2:3], v33, v16
	v_or_b32_e32 v33, 2, v13
	v_or_b32_e32 v31, s6, v11
	v_writelane_b32 v255, s2, 3
	s_lshl_b32 s6, s5, 5
	s_and_b32 s6, s6, 0xe0
	v_writelane_b32 v255, s3, 4
	v_cmp_lt_i32_e64 s[2:3], v33, v16
	v_mul_lo_u32 v31, v31, s54
	s_add_i32 s6, s6, 0
	v_writelane_b32 v255, s2, 5
	v_readlane_b32 s78, v251, 47
	v_or_b32_e32 v14, s7, v11
	v_writelane_b32 v255, s3, 6
	v_cmp_gt_i32_e64 s[2:3], v33, v16
	v_or_b32_e32 v33, 3, v13
	v_add_u32_e32 v31, s6, v31
	v_writelane_b32 v255, s2, 7
	s_lshl_b32 s86, s5, 10
	v_readlane_b32 s79, v251, 48
	v_writelane_b32 v255, s3, 8
	v_cmp_lt_i32_e64 s[2:3], v33, v16
	v_mul_lo_u32 v14, v14, s54
	v_mad_u32_u24 v17, v16, s54, 0
	v_writelane_b32 v255, s2, 9
	v_mad_u32_u24 v18, v16, s54, v18
	v_mul_lo_u32 v26, v82, s54
	v_writelane_b32 v255, s3, 10
	v_cmp_gt_i32_e64 s[2:3], v33, v16
	v_or_b32_e32 v33, 8, v13
	v_mul_lo_u32 v27, v84, s54
	v_writelane_b32 v255, s2, 11
	v_cmp_lt_i32_e64 s[54:55], v13, v16
	v_lshl_add_u64 v[90:91], s[78:79], 0, v[4:5]
	v_writelane_b32 v255, s3, 12
	v_cmp_lt_i32_e64 s[2:3], v33, v16
	v_readlane_b32 s78, v251, 51
	v_and_b32_e32 v2, 63, v70
	v_writelane_b32 v255, s2, 15
	v_lshl_add_u32 v3, v72, 7, 0
	v_add_u32_e32 v9, 0, v6
	v_writelane_b32 v255, s3, 16
	v_cmp_gt_i32_e64 s[2:3], v33, v16
	v_or_b32_e32 v33, 9, v13
	v_add_u32_e32 v14, 0, v14
	v_writelane_b32 v255, s2, 17
	v_lshl_or_b32 v10, v86, 1, v10
	v_mul_u32_u24_e32 v11, 0x90, v11
	v_writelane_b32 v255, s3, 18
	v_cmp_lt_i32_e64 s[2:3], v33, v16
	v_readlane_b32 s79, v251, 52
	v_readlane_b32 s67, v252, 54
	v_writelane_b32 v255, s2, 19
	v_mov_b32_e32 v71, v131
	v_lshlrev_b32_e32 v88, 4, v2
	v_writelane_b32 v255, s3, 20
	v_cmp_gt_i32_e64 s[2:3], v33, v16
	v_or_b32_e32 v33, 10, v13
	v_mov_b32_e32 v89, v131
	v_writelane_b32 v255, s2, 21
	s_ashr_i32 s73, s72, 31
	v_lshl_add_u64 v[92:93], s[78:79], 0, v[6:7]
	v_writelane_b32 v255, s3, 22
	v_cmp_lt_i32_e64 s[2:3], v33, v16
	v_lshl_add_u64 v[94:95], s[76:77], 0, v[130:131]
	s_lshl_b32 s67, s67, 6
	v_writelane_b32 v255, s2, 23
	s_lshl_b32 s87, s93, 6
	v_add_u32_e32 v107, v3, v130
	v_writelane_b32 v255, s3, 24
	v_cmp_gt_i32_e64 s[2:3], v33, v16
	v_or_b32_e32 v33, 11, v13
	v_add_u32_e32 v108, v8, v22
	v_writelane_b32 v255, s2, 25
	v_add_u32_e32 v109, v8, v23
	v_add_u32_e32 v110, v8, v24
	v_writelane_b32 v255, s3, 26
	v_cmp_lt_i32_e64 s[2:3], v33, v16
	v_add_u32_e32 v111, v8, v25
	v_add_u32_e32 v112, v9, v26
	v_writelane_b32 v255, s2, 27
	v_add_u32_e32 v113, v9, v27
	v_add_u32_e32 v114, 0, v10
	v_writelane_b32 v255, s3, 28
	v_cmp_gt_i32_e64 s[2:3], v33, v16
	v_or_b32_e32 v33, 16, v13
	v_add_u32_e32 v115, v28, v12
	v_writelane_b32 v255, s2, 29
	v_add_u32_e32 v116, v29, v12
	v_add_u32_e32 v117, v30, v12
	v_writelane_b32 v255, s3, 30
	v_cmp_lt_i32_e64 s[2:3], v33, v16
	v_add_u32_e32 v118, v31, v12
	v_add_u32_e32 v119, v17, v15
	v_writelane_b32 v255, s2, 31
	v_add_u32_e32 v120, v18, v15
	v_add_u32_e32 v121, v19, v32
	v_writelane_b32 v255, s3, 32
	v_cmp_gt_i32_e64 s[2:3], v33, v16
	v_or_b32_e32 v33, 17, v13
	v_add_u32_e32 v123, v21, v11
	v_writelane_b32 v255, s2, 33
	v_lshlrev_b32_e32 v130, 3, v2
	v_add_u32_e32 v124, v14, v15
	v_writelane_b32 v255, s3, 34
	v_cmp_lt_i32_e64 s[2:3], v33, v16
	v_readlane_b32 s76, v254, 16
	s_nop 0
	v_writelane_b32 v255, s2, 35
	s_nop 1
	v_writelane_b32 v255, s3, 36
	v_cmp_gt_i32_e64 s[2:3], v33, v16
	v_or_b32_e32 v33, 18, v13
	v_cmp_gt_i32_e64 s[94:95], v33, v16
	v_writelane_b32 v255, s2, 37
	s_nop 1
	v_writelane_b32 v255, s3, 38
	v_cmp_lt_i32_e64 s[2:3], v33, v16
	v_or_b32_e32 v33, 19, v13
	v_cmp_lt_i32_e64 s[68:69], v33, v16
	v_writelane_b32 v255, s2, 39
	s_nop 1
	v_writelane_b32 v255, s3, 40
	v_cmp_gt_i32_e64 s[2:3], v33, v16
	v_or_b32_e32 v33, 24, v13
	v_cmp_lt_i32_e64 s[4:5], v33, v16
	v_cmp_gt_i32_e64 s[6:7], v33, v16
	v_or_b32_e32 v33, 25, v13
	v_cmp_lt_i32_e64 s[60:61], v33, v16
	v_cmp_gt_i32_e64 s[62:63], v33, v16
	v_or_b32_e32 v33, 26, v13
	v_or_b32_e32 v13, 27, v13
	v_cmp_lt_i32_e64 s[56:57], v13, v16
	v_cmp_gt_i32_e64 s[58:59], v13, v16
	v_mul_u32_u24_e32 v13, 0x210, v12
	v_cmp_lt_i32_e64 s[64:65], v33, v16
	v_cmp_gt_i32_e64 s[82:83], v33, v16
	v_add_u32_e32 v122, v20, v13
	s_waitcnt vmcnt(0)
	s_nop 0
	s_branch .LBB0_423
